# k11 + rmsnorm phase loop rewritten: shift/scale table staged in LDS per WG, x rows prefetched 4 deep with counted vmcnt
# speedup vs baseline: 1.0139x; 1.0090x over previous
.LBB0_253:
	s_mov_b64 s[92:93], 0
	s_mov_b32 s0, s57
	s_mul_hi_u32 s1, s20, 3
	v_writelane_b32 v254, s0, 40
	s_mov_b32 s0, -1
	v_readlane_b32 s3, v254, 37
	v_mbcnt_lo_u32_b32 v0, s0, 0
	v_mbcnt_hi_u32_b32 v240, s0, v0
	s_mul_i32 s0, s20, 3
	s_add_u32 s0, s0, s3
	s_addc_u32 s1, s1, 0
	s_lshl_b64 s[0:1], s[0:1], 12
	s_add_u32 s0, s10, s0
	s_mov_b64 s[8:9], s[4:5]
	s_mov_b64 s[14:15], s[10:11]
	s_mov_b64 s[22:23], s[18:19]
	v_writelane_b32 v254, s8, 3
	s_addc_u32 s1, s11, s1
	v_lshlrev_b32_e32 v0, 4, v240
	global_load_dwordx4 v[2:5], v0, s[0:1]
	global_load_dwordx4 v[6:9], v0, s[0:1] offset:1024
	s_waitcnt lgkmcnt(0)
	global_load_dwordx4 v[10:13], v0, s[0:1] offset:2048
	global_load_dwordx4 v[14:17], v0, s[0:1] offset:3072
	v_writelane_b32 v254, s9, 4
	v_writelane_b32 v254, s10, 5
	v_writelane_b32 v254, s11, 6
	v_writelane_b32 v254, s12, 7
	v_writelane_b32 v254, s13, 8
	v_writelane_b32 v254, s14, 9
	v_writelane_b32 v254, s15, 10
	v_writelane_b32 v254, s16, 11
	v_writelane_b32 v254, s17, 12
	v_writelane_b32 v254, s18, 13
	v_writelane_b32 v254, s19, 14
	v_writelane_b32 v254, s20, 15
	v_writelane_b32 v254, s21, 16
	v_writelane_b32 v254, s22, 17
	v_writelane_b32 v254, s23, 18
	s_mul_i32 s0, s3, 0x3000
	v_readlane_b32 s2, v254, 31
	s_mul_hi_u32 s1, s3, 0x3000
	s_add_u32 s0, s2, s0
	v_readlane_b32 s2, v254, 33
	s_waitcnt vmcnt(6)
	v_cndmask_b32_e64 v18, 0, 1, s[58:59]
	s_addc_u32 s1, s2, s1
	v_cmp_ne_u32_e64 s[2:3], 1, v18
	v_mov_b32_e32 v50, 0
	s_andn2_b64 vcc, exec, s[58:59]
	v_writelane_b32 v254, s2, 23
	v_mov_b32_e32 v51, v50
	v_mov_b32_e32 v52, v50
	v_writelane_b32 v254, s3, 24
	v_mov_b32_e32 v53, v50
	v_mov_b32_e32 v62, v50
	v_mov_b32_e32 v63, v50
	v_mov_b32_e32 v64, v50
	v_mov_b32_e32 v65, v50
	v_mov_b32_e32 v58, v50
	v_mov_b32_e32 v59, v50
	v_mov_b32_e32 v60, v50
	v_mov_b32_e32 v61, v50
	v_mov_b32_e32 v46, v50
	v_mov_b32_e32 v47, v50
	v_mov_b32_e32 v48, v50
	v_mov_b32_e32 v49, v50
	v_lshlrev_b32_e32 v0, 4, v240
	v_readlane_b32 s40, v254, 35
	v_readlane_b32 s41, v254, 36
	s_and_b32 s46, s88, 7
	s_mul_i32 s43, s46, 0x12000
	s_add_u32 s48, s0, s43
	s_addc_u32 s49, s1, 0
	s_add_u32 s50, s48, 0x1000
	s_addc_u32 s51, s49, 0
	global_load_dwordx4 v[18:21], v0, s[48:49]
	global_load_dwordx4 v[22:25], v0, s[48:49] offset:1024
	global_load_dwordx4 v[26:29], v0, s[48:49] offset:2048
	global_load_dwordx4 v[30:33], v0, s[48:49] offset:3072
	global_load_dwordx4 v[34:37], v0, s[50:51]
	global_load_dwordx4 v[38:41], v0, s[50:51] offset:1024
	global_load_dwordx4 v[42:45], v0, s[50:51] offset:2048
	global_load_dwordx4 v[46:49], v0, s[50:51] offset:3072
	s_add_u32 s48, s48, 0x9000
	s_addc_u32 s49, s49, 0
	s_add_u32 s50, s50, 0x9000
	s_addc_u32 s51, s51, 0
	global_load_dwordx4 v[50:53], v0, s[48:49]
	global_load_dwordx4 v[54:57], v0, s[48:49] offset:1024
	global_load_dwordx4 v[58:61], v0, s[48:49] offset:2048
	global_load_dwordx4 v[62:65], v0, s[48:49] offset:3072
	global_load_dwordx4 v[140:143], v0, s[50:51]
	global_load_dwordx4 v[144:147], v0, s[50:51] offset:1024
	global_load_dwordx4 v[148:151], v0, s[50:51] offset:2048
	global_load_dwordx4 v[152:155], v0, s[50:51] offset:3072
	s_mov_b32 s4, s88
	s_mov_b32 s42, s88
	s_cmp_lt_i32 s42, 0x8000
	s_cselect_b64 exec, -1, 1
	s_min_i32 s43, s42, 0x7fff
	s_lshl_b32 s43, s43, 12
	s_add_u32 s44, s40, s43
	s_addc_u32 s45, s41, 0
	global_load_dwordx4 v[66:69], v0, s[44:45] nt
	global_load_dwordx4 v[70:73], v0, s[44:45] offset:1024 nt
	global_load_dwordx4 v[74:77], v0, s[44:45] offset:2048 nt
	global_load_dwordx4 v[78:81], v0, s[44:45] offset:3072 nt
	s_mov_b64 exec, -1
	s_add_i32 s42, s42, s90
	s_mov_b64 exec, 1
	global_load_dword v136, v0, s[40:41]
	global_load_dword v136, v0, s[40:41]
	global_load_dword v136, v0, s[40:41]
	global_load_dword v136, v0, s[40:41]
	s_mov_b64 exec, -1
	s_cmp_lt_i32 s42, 0x8000
	s_cselect_b64 exec, -1, 1
	s_min_i32 s43, s42, 0x7fff
	s_lshl_b32 s43, s43, 12
	s_add_u32 s44, s40, s43
	s_addc_u32 s45, s41, 0
	global_load_dwordx4 v[82:85], v0, s[44:45] nt
	global_load_dwordx4 v[86:89], v0, s[44:45] offset:1024 nt
	global_load_dwordx4 v[90:93], v0, s[44:45] offset:2048 nt
	global_load_dwordx4 v[94:97], v0, s[44:45] offset:3072 nt
	s_mov_b64 exec, -1
	s_add_i32 s42, s42, s90
	s_mov_b64 exec, 1
	global_load_dword v136, v0, s[40:41]
	global_load_dword v136, v0, s[40:41]
	global_load_dword v136, v0, s[40:41]
	global_load_dword v136, v0, s[40:41]
	s_mov_b64 exec, -1
	s_cmp_lt_i32 s42, 0x8000
	s_cselect_b64 exec, -1, 1
	s_min_i32 s43, s42, 0x7fff
	s_lshl_b32 s43, s43, 12
	s_add_u32 s44, s40, s43
	s_addc_u32 s45, s41, 0
	global_load_dwordx4 v[98:101], v0, s[44:45] nt
	global_load_dwordx4 v[102:105], v0, s[44:45] offset:1024 nt
	global_load_dwordx4 v[106:109], v0, s[44:45] offset:2048 nt
	global_load_dwordx4 v[110:113], v0, s[44:45] offset:3072 nt
	s_mov_b64 exec, -1
	s_add_i32 s42, s42, s90
	s_mov_b64 exec, 1
	global_load_dword v136, v0, s[40:41]
	global_load_dword v136, v0, s[40:41]
	global_load_dword v136, v0, s[40:41]
	global_load_dword v136, v0, s[40:41]
	s_mov_b64 exec, -1
	s_cmp_lt_i32 s42, 0x8000
	s_cselect_b64 exec, -1, 1
	s_min_i32 s43, s42, 0x7fff
	s_lshl_b32 s43, s43, 12
	s_add_u32 s44, s40, s43
	s_addc_u32 s45, s41, 0
	global_load_dwordx4 v[118:121], v0, s[44:45] nt
	global_load_dwordx4 v[122:125], v0, s[44:45] offset:1024 nt
	global_load_dwordx4 v[126:129], v0, s[44:45] offset:2048 nt
	global_load_dwordx4 v[130:133], v0, s[44:45] offset:3072 nt
	s_mov_b64 exec, -1
	s_add_i32 s42, s42, s90
	s_mov_b64 exec, 1
	global_load_dword v136, v0, s[40:41]
	global_load_dword v136, v0, s[40:41]
	global_load_dword v136, v0, s[40:41]
	global_load_dword v136, v0, s[40:41]
	s_mov_b64 exec, -1
	s_lshl_b32 s43, s46, 14
	v_add_u32_e32 v134, s43, v0
	s_waitcnt vmcnt(32)
	ds_write_b128 v134, v[18:21]
	ds_write_b128 v134, v[22:25] offset:1024
	ds_write_b128 v134, v[26:29] offset:2048
	ds_write_b128 v134, v[30:33] offset:3072
	ds_write_b128 v134, v[34:37] offset:4096
	ds_write_b128 v134, v[38:41] offset:5120
	ds_write_b128 v134, v[42:45] offset:6144
	ds_write_b128 v134, v[46:49] offset:7168
	s_waitcnt lgkmcnt(0)
	ds_write_b128 v134, v[50:53] offset:8192
	ds_write_b128 v134, v[54:57] offset:9216
	ds_write_b128 v134, v[58:61] offset:10240
	ds_write_b128 v134, v[62:65] offset:11264
	ds_write_b128 v134, v[140:143] offset:12288
	ds_write_b128 v134, v[144:147] offset:13312
	ds_write_b128 v134, v[148:151] offset:14336
	ds_write_b128 v134, v[152:155] offset:15360
	s_waitcnt lgkmcnt(0)
	v_readlane_b32 s0, v253, 28
	s_add_u32 s0, s0, s92
	v_readlane_b32 s1, v253, 29
	s_addc_u32 s1, s1, s93
	v_lshlrev_b32_e32 v134, 3, v240
	v_mov_b32_e32 v135, 0
	v_lshl_add_u64 v[114:115], s[0:1], 0, v[134:135]
	v_xor_b32_e32 v116, 1, v240
	v_lshlrev_b32_e32 v116, 2, v116
	v_xor_b32_e32 v117, 2, v240
	v_lshlrev_b32_e32 v117, 2, v117
	v_xor_b32_e32 v152, 4, v240
	v_lshlrev_b32_e32 v152, 2, v152
	v_xor_b32_e32 v153, 8, v240
	v_lshlrev_b32_e32 v153, 2, v153
	v_xor_b32_e32 v154, 16, v240
	v_lshlrev_b32_e32 v154, 2, v154
	v_xor_b32_e32 v155, 32, v240
	v_lshlrev_b32_e32 v155, 2, v155
	s_barrier
.Lnorm_loop:
	s_lshr_b32 s43, s4, 11
	s_lshl_b32 s43, s43, 13
	v_add_u32_e32 v156, s43, v0
	ds_read_b128 v[42:45], v156
	ds_read_b128 v[30:33], v156 offset:1024
	ds_read_b128 v[26:29], v156 offset:2048
	ds_read_b128 v[18:21], v156 offset:3072
	ds_read_b128 v[54:57], v156 offset:4096
	ds_read_b128 v[38:41], v156 offset:5120
	ds_read_b128 v[34:37], v156 offset:6144
	ds_read_b128 v[22:25], v156 offset:7168
	s_waitcnt vmcnt(28)
	v_mov_b32_e32 v50, v66
	v_mov_b32_e32 v51, v67
	v_mov_b32_e32 v52, v68
	v_mov_b32_e32 v53, v69
	v_mov_b32_e32 v62, v70
	v_mov_b32_e32 v63, v71
	v_mov_b32_e32 v64, v72
	v_mov_b32_e32 v65, v73
	v_mov_b32_e32 v58, v74
	v_mov_b32_e32 v59, v75
	v_mov_b32_e32 v60, v76
	v_mov_b32_e32 v61, v77
	v_mov_b32_e32 v46, v78
	v_mov_b32_e32 v47, v79
	v_mov_b32_e32 v48, v80
	v_mov_b32_e32 v49, v81
	s_cmp_lt_i32 s42, 0x8000
	s_cselect_b64 exec, -1, 1
	s_min_i32 s43, s42, 0x7fff
	s_lshl_b32 s43, s43, 12
	s_add_u32 s44, s40, s43
	s_addc_u32 s45, s41, 0
	global_load_dwordx4 v[66:69], v0, s[44:45] nt
	global_load_dwordx4 v[70:73], v0, s[44:45] offset:1024 nt
	global_load_dwordx4 v[74:77], v0, s[44:45] offset:2048 nt
	global_load_dwordx4 v[78:81], v0, s[44:45] offset:3072 nt
	s_mov_b64 exec, -1
	s_add_i32 s42, s42, s90
	s_waitcnt lgkmcnt(0)
	v_pk_mul_f32 v[146:147], v[52:53], v[52:53]
	v_pk_mul_f32 v[148:149], v[50:51], v[50:51]
	v_pk_mul_f32 v[142:143], v[64:65], v[64:65]
	v_pk_mul_f32 v[144:145], v[62:63], v[62:63]
	v_pk_mov_b32 v[150:151], v[148:149], v[146:147] op_sel:[1,0]
	v_mov_b32_e32 v149, v147
	v_pk_add_f32 v[146:147], v[150:151], v[148:149]
	v_pk_mov_b32 v[148:149], v[144:145], v[142:143] op_sel:[1,0]
	v_mov_b32_e32 v145, v143
	v_pk_add_f32 v[142:143], v[148:149], v[144:145]
	v_pk_add_f32 v[146:147], v[146:147], v[146:147] op_sel_hi:[0,1]
	v_pk_add_f32 v[142:143], v[142:143], v[142:143] op_sel_hi:[0,1]
	v_mul_f32_e32 v142, v58, v58
	v_pk_fma_f32 v[144:145], v[58:59], v[58:59], v[142:143] op_sel_hi:[1,1,0]
	v_mul_f32_e32 v142, v60, v60
	v_pk_fma_f32 v[148:149], v[60:61], v[60:61], v[142:143] op_sel_hi:[1,1,0]
	v_mul_f32_e32 v144, v46, v46
	v_mul_f32_e32 v148, v47, v47
	v_mul_f32_e32 v146, v48, v48
	v_mul_f32_e32 v142, v49, v49
	v_pk_add_f32 v[144:145], v[144:145], v[148:149]
	v_pk_add_f32 v[142:143], v[146:147], v[142:143]
	s_mov_b32 s0, 0xf800000
	v_pk_add_f32 v[142:143], v[144:145], v[142:143]
	v_pk_add_f32 v[56:57], v[56:57], 1.0 op_sel_hi:[1,0]
	v_add_f32_e32 v141, v142, v143
	ds_bpermute_b32 v142, v116, v141
	v_mov_b32_e32 v143, 0x358637bd
	v_pk_add_f32 v[54:55], v[54:55], 1.0 op_sel_hi:[1,0]
	v_pk_add_f32 v[40:41], v[40:41], 1.0 op_sel_hi:[1,0]
	v_pk_add_f32 v[38:39], v[38:39], 1.0 op_sel_hi:[1,0]
	s_waitcnt lgkmcnt(0)
	v_add_f32_e32 v141, v141, v142
	ds_bpermute_b32 v142, v117, v141
	v_pk_add_f32 v[36:37], v[36:37], 1.0 op_sel_hi:[1,0]
	v_pk_add_f32 v[34:35], v[34:35], 1.0 op_sel_hi:[1,0]
	v_pk_add_f32 v[24:25], v[24:25], 1.0 op_sel_hi:[1,0]
	v_pk_add_f32 v[22:23], v[22:23], 1.0 op_sel_hi:[1,0]
	s_waitcnt lgkmcnt(0)
	v_add_f32_e32 v141, v141, v142
	ds_bpermute_b32 v142, v152, v141
	s_nop 0
	s_nop 0
	s_nop 0
	s_nop 0
	s_waitcnt lgkmcnt(0)
	v_add_f32_e32 v141, v141, v142
	ds_bpermute_b32 v142, v153, v141
	s_nop 0
	s_nop 0
	s_nop 0
	s_nop 0
	s_waitcnt lgkmcnt(0)
	v_add_f32_e32 v141, v141, v142
	ds_bpermute_b32 v142, v154, v141
	s_nop 0
	s_waitcnt lgkmcnt(0)
	v_add_f32_e32 v141, v141, v142
	ds_bpermute_b32 v142, v155, v141
	s_waitcnt lgkmcnt(0)
	v_add_f32_e32 v141, v141, v142
	v_fmamk_f32 v141, v141, 0x3a800000, v143
	v_mul_f32_e32 v142, 0x4f800000, v141
	v_cmp_gt_f32_e32 vcc, s0, v141
	v_mov_b32_e32 v143, 0x260
	s_nop 0
	v_cndmask_b32_e32 v141, v141, v142, vcc
	v_sqrt_f32_e32 v142, v141
	s_nop 0
	v_add_u32_e32 v144, -1, v142
	v_add_u32_e32 v145, 1, v142
	v_fma_f32 v146, -v144, v142, v141
	v_fma_f32 v147, -v145, v142, v141
	v_cmp_ge_f32_e64 s[0:1], 0, v146
	s_nop 1
	v_cndmask_b32_e64 v142, v142, v144, s[0:1]
	v_cmp_lt_f32_e64 s[0:1], 0, v147
	s_nop 0
	s_nop 0
	v_cndmask_b32_e64 v142, v142, v145, s[0:1]
	v_mul_f32_e32 v144, 0x37800000, v142
	v_cndmask_b32_e32 v142, v142, v144, vcc
	v_cmp_class_f32_e32 vcc, v141, v143
	s_nop 1
	v_cndmask_b32_e32 v141, v142, v141, vcc
	v_div_scale_f32 v142, s[0:1], v141, v141, 1.0
	v_rcp_f32_e32 v143, v142
	v_div_scale_f32 v144, vcc, 1.0, v141, 1.0
	v_readlane_b32 s0, v253, 30
	v_fma_f32 v145, -v142, v143, 1.0
	v_fmac_f32_e32 v143, v145, v143
	v_mul_f32_e32 v145, v144, v143
	v_fma_f32 v146, -v142, v145, v144
	v_fmac_f32_e32 v145, v146, v143
	v_fma_f32 v142, -v142, v145, v144
	v_div_fmas_f32 v142, v142, v143, v145
	v_div_fixup_f32 v142, v142, v141, 1.0
	v_pk_mul_f32 v[52:53], v[52:53], v[142:143] op_sel_hi:[1,0]
	v_pk_mul_f32 v[50:51], v[50:51], v[142:143] op_sel_hi:[1,0]
	v_pk_mul_f32 v[52:53], v[4:5], v[52:53]
	v_pk_mul_f32 v[50:51], v[2:3], v[50:51]
	v_pk_fma_f32 v[44:45], v[56:57], v[52:53], v[44:45]
	v_pk_fma_f32 v[42:43], v[54:55], v[50:51], v[42:43]
	v_readlane_b32 s1, v253, 31
	v_cvt_pk_bf16_f32 v42, v42, v43
	v_cvt_pk_bf16_f32 v43, v44, v45
	global_store_dwordx2 v[114:115], v[42:43], off offset:-1024
	v_pk_mul_f32 v[42:43], v[64:65], v[142:143] op_sel_hi:[1,0]
	v_pk_mul_f32 v[44:45], v[62:63], v[142:143] op_sel_hi:[1,0]
	v_pk_mul_f32 v[42:43], v[8:9], v[42:43]
	v_pk_mul_f32 v[44:45], v[6:7], v[44:45]
	v_pk_fma_f32 v[32:33], v[40:41], v[42:43], v[32:33]
	v_pk_fma_f32 v[30:31], v[38:39], v[44:45], v[30:31]
	s_nop 0
	v_cvt_pk_bf16_f32 v30, v30, v31
	v_cvt_pk_bf16_f32 v31, v32, v33
	global_store_dwordx2 v[114:115], v[30:31], off offset:-512
	v_pk_mul_f32 v[30:31], v[60:61], v[142:143] op_sel_hi:[1,0]
	v_pk_mul_f32 v[32:33], v[58:59], v[142:143] op_sel_hi:[1,0]
	v_pk_mul_f32 v[30:31], v[12:13], v[30:31]
	v_pk_mul_f32 v[32:33], v[10:11], v[32:33]
	v_pk_fma_f32 v[28:29], v[36:37], v[30:31], v[28:29]
	v_pk_fma_f32 v[26:27], v[34:35], v[32:33], v[26:27]
	s_nop 0
	v_cvt_pk_bf16_f32 v26, v26, v27
	v_cvt_pk_bf16_f32 v27, v28, v29
	global_store_dwordx2 v[114:115], v[26:27], off
	v_pk_mul_f32 v[26:27], v[48:49], v[142:143] op_sel_hi:[1,0]
	v_pk_mul_f32 v[28:29], v[46:47], v[142:143] op_sel_hi:[1,0]
	v_pk_mul_f32 v[26:27], v[16:17], v[26:27]
	v_pk_mul_f32 v[28:29], v[14:15], v[28:29]
	v_pk_fma_f32 v[20:21], v[24:25], v[26:27], v[20:21]
	v_pk_fma_f32 v[18:19], v[22:23], v[28:29], v[18:19]
	s_nop 0
	v_cvt_pk_bf16_f32 v18, v18, v19
	v_cvt_pk_bf16_f32 v19, v20, v21
	global_store_dwordx2 v[114:115], v[18:19], off offset:512
	v_lshl_add_u64 v[114:115], v[114:115], 0, s[0:1]
	s_add_i32 s4, s4, s90
	s_cmp_lt_i32 s4, 0x8000
	s_cbranch_scc0 .Lnorm_done
	s_lshr_b32 s43, s4, 11
	s_lshl_b32 s43, s43, 13
	v_add_u32_e32 v156, s43, v0
	ds_read_b128 v[42:45], v156
	ds_read_b128 v[30:33], v156 offset:1024
	ds_read_b128 v[26:29], v156 offset:2048
	ds_read_b128 v[18:21], v156 offset:3072
	ds_read_b128 v[54:57], v156 offset:4096
	ds_read_b128 v[38:41], v156 offset:5120
	ds_read_b128 v[34:37], v156 offset:6144
	ds_read_b128 v[22:25], v156 offset:7168
	s_waitcnt vmcnt(28)
	v_mov_b32_e32 v50, v82
	v_mov_b32_e32 v51, v83
	v_mov_b32_e32 v52, v84
	v_mov_b32_e32 v53, v85
	v_mov_b32_e32 v62, v86
	v_mov_b32_e32 v63, v87
	v_mov_b32_e32 v64, v88
	v_mov_b32_e32 v65, v89
	v_mov_b32_e32 v58, v90
	v_mov_b32_e32 v59, v91
	v_mov_b32_e32 v60, v92
	v_mov_b32_e32 v61, v93
	v_mov_b32_e32 v46, v94
	v_mov_b32_e32 v47, v95
	v_mov_b32_e32 v48, v96
	v_mov_b32_e32 v49, v97
	s_cmp_lt_i32 s42, 0x8000
	s_cselect_b64 exec, -1, 1
	s_min_i32 s43, s42, 0x7fff
	s_lshl_b32 s43, s43, 12
	s_add_u32 s44, s40, s43
	s_addc_u32 s45, s41, 0
	global_load_dwordx4 v[82:85], v0, s[44:45] nt
	global_load_dwordx4 v[86:89], v0, s[44:45] offset:1024 nt
	global_load_dwordx4 v[90:93], v0, s[44:45] offset:2048 nt
	global_load_dwordx4 v[94:97], v0, s[44:45] offset:3072 nt
	s_mov_b64 exec, -1
	s_add_i32 s42, s42, s90
	s_waitcnt lgkmcnt(0)
	v_pk_mul_f32 v[146:147], v[52:53], v[52:53]
	v_pk_mul_f32 v[148:149], v[50:51], v[50:51]
	v_pk_mul_f32 v[142:143], v[64:65], v[64:65]
	v_pk_mul_f32 v[144:145], v[62:63], v[62:63]
	v_pk_mov_b32 v[150:151], v[148:149], v[146:147] op_sel:[1,0]
	v_mov_b32_e32 v149, v147
	v_pk_add_f32 v[146:147], v[150:151], v[148:149]
	v_pk_mov_b32 v[148:149], v[144:145], v[142:143] op_sel:[1,0]
	v_mov_b32_e32 v145, v143
	v_pk_add_f32 v[142:143], v[148:149], v[144:145]
	v_pk_add_f32 v[146:147], v[146:147], v[146:147] op_sel_hi:[0,1]
	v_pk_add_f32 v[142:143], v[142:143], v[142:143] op_sel_hi:[0,1]
	v_mul_f32_e32 v142, v58, v58
	v_pk_fma_f32 v[144:145], v[58:59], v[58:59], v[142:143] op_sel_hi:[1,1,0]
	v_mul_f32_e32 v142, v60, v60
	v_pk_fma_f32 v[148:149], v[60:61], v[60:61], v[142:143] op_sel_hi:[1,1,0]
	v_mul_f32_e32 v144, v46, v46
	v_mul_f32_e32 v148, v47, v47
	v_mul_f32_e32 v146, v48, v48
	v_mul_f32_e32 v142, v49, v49
	v_pk_add_f32 v[144:145], v[144:145], v[148:149]
	v_pk_add_f32 v[142:143], v[146:147], v[142:143]
	s_mov_b32 s0, 0xf800000
	v_pk_add_f32 v[142:143], v[144:145], v[142:143]
	v_pk_add_f32 v[56:57], v[56:57], 1.0 op_sel_hi:[1,0]
	v_add_f32_e32 v141, v142, v143
	ds_bpermute_b32 v142, v116, v141
	v_mov_b32_e32 v143, 0x358637bd
	v_pk_add_f32 v[54:55], v[54:55], 1.0 op_sel_hi:[1,0]
	v_pk_add_f32 v[40:41], v[40:41], 1.0 op_sel_hi:[1,0]
	v_pk_add_f32 v[38:39], v[38:39], 1.0 op_sel_hi:[1,0]
	s_waitcnt lgkmcnt(0)
	v_add_f32_e32 v141, v141, v142
	ds_bpermute_b32 v142, v117, v141
	v_pk_add_f32 v[36:37], v[36:37], 1.0 op_sel_hi:[1,0]
	v_pk_add_f32 v[34:35], v[34:35], 1.0 op_sel_hi:[1,0]
	v_pk_add_f32 v[24:25], v[24:25], 1.0 op_sel_hi:[1,0]
	v_pk_add_f32 v[22:23], v[22:23], 1.0 op_sel_hi:[1,0]
	s_waitcnt lgkmcnt(0)
	v_add_f32_e32 v141, v141, v142
	ds_bpermute_b32 v142, v152, v141
	s_nop 0
	s_nop 0
	s_nop 0
	s_nop 0
	s_waitcnt lgkmcnt(0)
	v_add_f32_e32 v141, v141, v142
	ds_bpermute_b32 v142, v153, v141
	s_nop 0
	s_nop 0
	s_nop 0
	s_nop 0
	s_waitcnt lgkmcnt(0)
	v_add_f32_e32 v141, v141, v142
	ds_bpermute_b32 v142, v154, v141
	s_nop 0
	s_waitcnt lgkmcnt(0)
	v_add_f32_e32 v141, v141, v142
	ds_bpermute_b32 v142, v155, v141
	s_waitcnt lgkmcnt(0)
	v_add_f32_e32 v141, v141, v142
	v_fmamk_f32 v141, v141, 0x3a800000, v143
	v_mul_f32_e32 v142, 0x4f800000, v141
	v_cmp_gt_f32_e32 vcc, s0, v141
	v_mov_b32_e32 v143, 0x260
	s_nop 0
	v_cndmask_b32_e32 v141, v141, v142, vcc
	v_sqrt_f32_e32 v142, v141
	s_nop 0
	v_add_u32_e32 v144, -1, v142
	v_add_u32_e32 v145, 1, v142
	v_fma_f32 v146, -v144, v142, v141
	v_fma_f32 v147, -v145, v142, v141
	v_cmp_ge_f32_e64 s[0:1], 0, v146
	s_nop 1
	v_cndmask_b32_e64 v142, v142, v144, s[0:1]
	v_cmp_lt_f32_e64 s[0:1], 0, v147
	s_nop 0
	s_nop 0
	v_cndmask_b32_e64 v142, v142, v145, s[0:1]
	v_mul_f32_e32 v144, 0x37800000, v142
	v_cndmask_b32_e32 v142, v142, v144, vcc
	v_cmp_class_f32_e32 vcc, v141, v143
	s_nop 1
	v_cndmask_b32_e32 v141, v142, v141, vcc
	v_div_scale_f32 v142, s[0:1], v141, v141, 1.0
	v_rcp_f32_e32 v143, v142
	v_div_scale_f32 v144, vcc, 1.0, v141, 1.0
	v_readlane_b32 s0, v253, 30
	v_fma_f32 v145, -v142, v143, 1.0
	v_fmac_f32_e32 v143, v145, v143
	v_mul_f32_e32 v145, v144, v143
	v_fma_f32 v146, -v142, v145, v144
	v_fmac_f32_e32 v145, v146, v143
	v_fma_f32 v142, -v142, v145, v144
	v_div_fmas_f32 v142, v142, v143, v145
	v_div_fixup_f32 v142, v142, v141, 1.0
	v_pk_mul_f32 v[52:53], v[52:53], v[142:143] op_sel_hi:[1,0]
	v_pk_mul_f32 v[50:51], v[50:51], v[142:143] op_sel_hi:[1,0]
	v_pk_mul_f32 v[52:53], v[4:5], v[52:53]
	v_pk_mul_f32 v[50:51], v[2:3], v[50:51]
	v_pk_fma_f32 v[44:45], v[56:57], v[52:53], v[44:45]
	v_pk_fma_f32 v[42:43], v[54:55], v[50:51], v[42:43]
	v_readlane_b32 s1, v253, 31
	v_cvt_pk_bf16_f32 v42, v42, v43
	v_cvt_pk_bf16_f32 v43, v44, v45
	global_store_dwordx2 v[114:115], v[42:43], off offset:-1024
	v_pk_mul_f32 v[42:43], v[64:65], v[142:143] op_sel_hi:[1,0]
	v_pk_mul_f32 v[44:45], v[62:63], v[142:143] op_sel_hi:[1,0]
	v_pk_mul_f32 v[42:43], v[8:9], v[42:43]
	v_pk_mul_f32 v[44:45], v[6:7], v[44:45]
	v_pk_fma_f32 v[32:33], v[40:41], v[42:43], v[32:33]
	v_pk_fma_f32 v[30:31], v[38:39], v[44:45], v[30:31]
	s_nop 0
	v_cvt_pk_bf16_f32 v30, v30, v31
	v_cvt_pk_bf16_f32 v31, v32, v33
	global_store_dwordx2 v[114:115], v[30:31], off offset:-512
	v_pk_mul_f32 v[30:31], v[60:61], v[142:143] op_sel_hi:[1,0]
	v_pk_mul_f32 v[32:33], v[58:59], v[142:143] op_sel_hi:[1,0]
	v_pk_mul_f32 v[30:31], v[12:13], v[30:31]
	v_pk_mul_f32 v[32:33], v[10:11], v[32:33]
	v_pk_fma_f32 v[28:29], v[36:37], v[30:31], v[28:29]
	v_pk_fma_f32 v[26:27], v[34:35], v[32:33], v[26:27]
	s_nop 0
	v_cvt_pk_bf16_f32 v26, v26, v27
	v_cvt_pk_bf16_f32 v27, v28, v29
	global_store_dwordx2 v[114:115], v[26:27], off
	v_pk_mul_f32 v[26:27], v[48:49], v[142:143] op_sel_hi:[1,0]
	v_pk_mul_f32 v[28:29], v[46:47], v[142:143] op_sel_hi:[1,0]
	v_pk_mul_f32 v[26:27], v[16:17], v[26:27]
	v_pk_mul_f32 v[28:29], v[14:15], v[28:29]
	v_pk_fma_f32 v[20:21], v[24:25], v[26:27], v[20:21]
	v_pk_fma_f32 v[18:19], v[22:23], v[28:29], v[18:19]
	s_nop 0
	v_cvt_pk_bf16_f32 v18, v18, v19
	v_cvt_pk_bf16_f32 v19, v20, v21
	global_store_dwordx2 v[114:115], v[18:19], off offset:512
	v_lshl_add_u64 v[114:115], v[114:115], 0, s[0:1]
	s_add_i32 s4, s4, s90
	s_cmp_lt_i32 s4, 0x8000
	s_cbranch_scc0 .Lnorm_done
	s_lshr_b32 s43, s4, 11
	s_lshl_b32 s43, s43, 13
	v_add_u32_e32 v156, s43, v0
	ds_read_b128 v[42:45], v156
	ds_read_b128 v[30:33], v156 offset:1024
	ds_read_b128 v[26:29], v156 offset:2048
	ds_read_b128 v[18:21], v156 offset:3072
	ds_read_b128 v[54:57], v156 offset:4096
	ds_read_b128 v[38:41], v156 offset:5120
	ds_read_b128 v[34:37], v156 offset:6144
	ds_read_b128 v[22:25], v156 offset:7168
	s_waitcnt vmcnt(28)
	v_mov_b32_e32 v50, v98
	v_mov_b32_e32 v51, v99
	v_mov_b32_e32 v52, v100
	v_mov_b32_e32 v53, v101
	v_mov_b32_e32 v62, v102
	v_mov_b32_e32 v63, v103
	v_mov_b32_e32 v64, v104
	v_mov_b32_e32 v65, v105
	v_mov_b32_e32 v58, v106
	v_mov_b32_e32 v59, v107
	v_mov_b32_e32 v60, v108
	v_mov_b32_e32 v61, v109
	v_mov_b32_e32 v46, v110
	v_mov_b32_e32 v47, v111
	v_mov_b32_e32 v48, v112
	v_mov_b32_e32 v49, v113
	s_cmp_lt_i32 s42, 0x8000
	s_cselect_b64 exec, -1, 1
	s_min_i32 s43, s42, 0x7fff
	s_lshl_b32 s43, s43, 12
	s_add_u32 s44, s40, s43
	s_addc_u32 s45, s41, 0
	global_load_dwordx4 v[98:101], v0, s[44:45] nt
	global_load_dwordx4 v[102:105], v0, s[44:45] offset:1024 nt
	global_load_dwordx4 v[106:109], v0, s[44:45] offset:2048 nt
	global_load_dwordx4 v[110:113], v0, s[44:45] offset:3072 nt
	s_mov_b64 exec, -1
	s_add_i32 s42, s42, s90
	s_waitcnt lgkmcnt(0)
	v_pk_mul_f32 v[146:147], v[52:53], v[52:53]
	v_pk_mul_f32 v[148:149], v[50:51], v[50:51]
	v_pk_mul_f32 v[142:143], v[64:65], v[64:65]
	v_pk_mul_f32 v[144:145], v[62:63], v[62:63]
	v_pk_mov_b32 v[150:151], v[148:149], v[146:147] op_sel:[1,0]
	v_mov_b32_e32 v149, v147
	v_pk_add_f32 v[146:147], v[150:151], v[148:149]
	v_pk_mov_b32 v[148:149], v[144:145], v[142:143] op_sel:[1,0]
	v_mov_b32_e32 v145, v143
	v_pk_add_f32 v[142:143], v[148:149], v[144:145]
	v_pk_add_f32 v[146:147], v[146:147], v[146:147] op_sel_hi:[0,1]
	v_pk_add_f32 v[142:143], v[142:143], v[142:143] op_sel_hi:[0,1]
	v_mul_f32_e32 v142, v58, v58
	v_pk_fma_f32 v[144:145], v[58:59], v[58:59], v[142:143] op_sel_hi:[1,1,0]
	v_mul_f32_e32 v142, v60, v60
	v_pk_fma_f32 v[148:149], v[60:61], v[60:61], v[142:143] op_sel_hi:[1,1,0]
	v_mul_f32_e32 v144, v46, v46
	v_mul_f32_e32 v148, v47, v47
	v_mul_f32_e32 v146, v48, v48
	v_mul_f32_e32 v142, v49, v49
	v_pk_add_f32 v[144:145], v[144:145], v[148:149]
	v_pk_add_f32 v[142:143], v[146:147], v[142:143]
	s_mov_b32 s0, 0xf800000
	v_pk_add_f32 v[142:143], v[144:145], v[142:143]
	v_pk_add_f32 v[56:57], v[56:57], 1.0 op_sel_hi:[1,0]
	v_add_f32_e32 v141, v142, v143
	ds_bpermute_b32 v142, v116, v141
	v_mov_b32_e32 v143, 0x358637bd
	v_pk_add_f32 v[54:55], v[54:55], 1.0 op_sel_hi:[1,0]
	v_pk_add_f32 v[40:41], v[40:41], 1.0 op_sel_hi:[1,0]
	v_pk_add_f32 v[38:39], v[38:39], 1.0 op_sel_hi:[1,0]
	s_waitcnt lgkmcnt(0)
	v_add_f32_e32 v141, v141, v142
	ds_bpermute_b32 v142, v117, v141
	v_pk_add_f32 v[36:37], v[36:37], 1.0 op_sel_hi:[1,0]
	v_pk_add_f32 v[34:35], v[34:35], 1.0 op_sel_hi:[1,0]
	v_pk_add_f32 v[24:25], v[24:25], 1.0 op_sel_hi:[1,0]
	v_pk_add_f32 v[22:23], v[22:23], 1.0 op_sel_hi:[1,0]
	s_waitcnt lgkmcnt(0)
	v_add_f32_e32 v141, v141, v142
	ds_bpermute_b32 v142, v152, v141
	s_nop 0
	s_nop 0
	s_nop 0
	s_nop 0
	s_waitcnt lgkmcnt(0)
	v_add_f32_e32 v141, v141, v142
	ds_bpermute_b32 v142, v153, v141
	s_nop 0
	s_nop 0
	s_nop 0
	s_nop 0
	s_waitcnt lgkmcnt(0)
	v_add_f32_e32 v141, v141, v142
	ds_bpermute_b32 v142, v154, v141
	s_nop 0
	s_waitcnt lgkmcnt(0)
	v_add_f32_e32 v141, v141, v142
	ds_bpermute_b32 v142, v155, v141
	s_waitcnt lgkmcnt(0)
	v_add_f32_e32 v141, v141, v142
	v_fmamk_f32 v141, v141, 0x3a800000, v143
	v_mul_f32_e32 v142, 0x4f800000, v141
	v_cmp_gt_f32_e32 vcc, s0, v141
	v_mov_b32_e32 v143, 0x260
	s_nop 0
	v_cndmask_b32_e32 v141, v141, v142, vcc
	v_sqrt_f32_e32 v142, v141
	s_nop 0
	v_add_u32_e32 v144, -1, v142
	v_add_u32_e32 v145, 1, v142
	v_fma_f32 v146, -v144, v142, v141
	v_fma_f32 v147, -v145, v142, v141
	v_cmp_ge_f32_e64 s[0:1], 0, v146
	s_nop 1
	v_cndmask_b32_e64 v142, v142, v144, s[0:1]
	v_cmp_lt_f32_e64 s[0:1], 0, v147
	s_nop 0
	s_nop 0
	v_cndmask_b32_e64 v142, v142, v145, s[0:1]
	v_mul_f32_e32 v144, 0x37800000, v142
	v_cndmask_b32_e32 v142, v142, v144, vcc
	v_cmp_class_f32_e32 vcc, v141, v143
	s_nop 1
	v_cndmask_b32_e32 v141, v142, v141, vcc
	v_div_scale_f32 v142, s[0:1], v141, v141, 1.0
	v_rcp_f32_e32 v143, v142
	v_div_scale_f32 v144, vcc, 1.0, v141, 1.0
	v_readlane_b32 s0, v253, 30
	v_fma_f32 v145, -v142, v143, 1.0
	v_fmac_f32_e32 v143, v145, v143
	v_mul_f32_e32 v145, v144, v143
	v_fma_f32 v146, -v142, v145, v144
	v_fmac_f32_e32 v145, v146, v143
	v_fma_f32 v142, -v142, v145, v144
	v_div_fmas_f32 v142, v142, v143, v145
	v_div_fixup_f32 v142, v142, v141, 1.0
	v_pk_mul_f32 v[52:53], v[52:53], v[142:143] op_sel_hi:[1,0]
	v_pk_mul_f32 v[50:51], v[50:51], v[142:143] op_sel_hi:[1,0]
	v_pk_mul_f32 v[52:53], v[4:5], v[52:53]
	v_pk_mul_f32 v[50:51], v[2:3], v[50:51]
	v_pk_fma_f32 v[44:45], v[56:57], v[52:53], v[44:45]
	v_pk_fma_f32 v[42:43], v[54:55], v[50:51], v[42:43]
	v_readlane_b32 s1, v253, 31
	v_cvt_pk_bf16_f32 v42, v42, v43
	v_cvt_pk_bf16_f32 v43, v44, v45
	global_store_dwordx2 v[114:115], v[42:43], off offset:-1024
	v_pk_mul_f32 v[42:43], v[64:65], v[142:143] op_sel_hi:[1,0]
	v_pk_mul_f32 v[44:45], v[62:63], v[142:143] op_sel_hi:[1,0]
	v_pk_mul_f32 v[42:43], v[8:9], v[42:43]
	v_pk_mul_f32 v[44:45], v[6:7], v[44:45]
	v_pk_fma_f32 v[32:33], v[40:41], v[42:43], v[32:33]
	v_pk_fma_f32 v[30:31], v[38:39], v[44:45], v[30:31]
	s_nop 0
	v_cvt_pk_bf16_f32 v30, v30, v31
	v_cvt_pk_bf16_f32 v31, v32, v33
	global_store_dwordx2 v[114:115], v[30:31], off offset:-512
	v_pk_mul_f32 v[30:31], v[60:61], v[142:143] op_sel_hi:[1,0]
	v_pk_mul_f32 v[32:33], v[58:59], v[142:143] op_sel_hi:[1,0]
	v_pk_mul_f32 v[30:31], v[12:13], v[30:31]
	v_pk_mul_f32 v[32:33], v[10:11], v[32:33]
	v_pk_fma_f32 v[28:29], v[36:37], v[30:31], v[28:29]
	v_pk_fma_f32 v[26:27], v[34:35], v[32:33], v[26:27]
	s_nop 0
	v_cvt_pk_bf16_f32 v26, v26, v27
	v_cvt_pk_bf16_f32 v27, v28, v29
	global_store_dwordx2 v[114:115], v[26:27], off
	v_pk_mul_f32 v[26:27], v[48:49], v[142:143] op_sel_hi:[1,0]
	v_pk_mul_f32 v[28:29], v[46:47], v[142:143] op_sel_hi:[1,0]
	v_pk_mul_f32 v[26:27], v[16:17], v[26:27]
	v_pk_mul_f32 v[28:29], v[14:15], v[28:29]
	v_pk_fma_f32 v[20:21], v[24:25], v[26:27], v[20:21]
	v_pk_fma_f32 v[18:19], v[22:23], v[28:29], v[18:19]
	s_nop 0
	v_cvt_pk_bf16_f32 v18, v18, v19
	v_cvt_pk_bf16_f32 v19, v20, v21
	global_store_dwordx2 v[114:115], v[18:19], off offset:512
	v_lshl_add_u64 v[114:115], v[114:115], 0, s[0:1]
	s_add_i32 s4, s4, s90
	s_cmp_lt_i32 s4, 0x8000
	s_cbranch_scc0 .Lnorm_done
	s_lshr_b32 s43, s4, 11
	s_lshl_b32 s43, s43, 13
	v_add_u32_e32 v156, s43, v0
	ds_read_b128 v[42:45], v156
	ds_read_b128 v[30:33], v156 offset:1024
	ds_read_b128 v[26:29], v156 offset:2048
	ds_read_b128 v[18:21], v156 offset:3072
	ds_read_b128 v[54:57], v156 offset:4096
	ds_read_b128 v[38:41], v156 offset:5120
	ds_read_b128 v[34:37], v156 offset:6144
	ds_read_b128 v[22:25], v156 offset:7168
	s_waitcnt vmcnt(28)
	v_mov_b32_e32 v50, v118
	v_mov_b32_e32 v51, v119
	v_mov_b32_e32 v52, v120
	v_mov_b32_e32 v53, v121
	v_mov_b32_e32 v62, v122
	v_mov_b32_e32 v63, v123
	v_mov_b32_e32 v64, v124
	v_mov_b32_e32 v65, v125
	v_mov_b32_e32 v58, v126
	v_mov_b32_e32 v59, v127
	v_mov_b32_e32 v60, v128
	v_mov_b32_e32 v61, v129
	v_mov_b32_e32 v46, v130
	v_mov_b32_e32 v47, v131
	v_mov_b32_e32 v48, v132
	v_mov_b32_e32 v49, v133
	s_cmp_lt_i32 s42, 0x8000
	s_cselect_b64 exec, -1, 1
	s_min_i32 s43, s42, 0x7fff
	s_lshl_b32 s43, s43, 12
	s_add_u32 s44, s40, s43
	s_addc_u32 s45, s41, 0
	global_load_dwordx4 v[118:121], v0, s[44:45] nt
	global_load_dwordx4 v[122:125], v0, s[44:45] offset:1024 nt
	global_load_dwordx4 v[126:129], v0, s[44:45] offset:2048 nt
	global_load_dwordx4 v[130:133], v0, s[44:45] offset:3072 nt
	s_mov_b64 exec, -1
	s_add_i32 s42, s42, s90
	s_waitcnt lgkmcnt(0)
	v_pk_mul_f32 v[146:147], v[52:53], v[52:53]
	v_pk_mul_f32 v[148:149], v[50:51], v[50:51]
	v_pk_mul_f32 v[142:143], v[64:65], v[64:65]
	v_pk_mul_f32 v[144:145], v[62:63], v[62:63]
	v_pk_mov_b32 v[150:151], v[148:149], v[146:147] op_sel:[1,0]
	v_mov_b32_e32 v149, v147
	v_pk_add_f32 v[146:147], v[150:151], v[148:149]
	v_pk_mov_b32 v[148:149], v[144:145], v[142:143] op_sel:[1,0]
	v_mov_b32_e32 v145, v143
	v_pk_add_f32 v[142:143], v[148:149], v[144:145]
	v_pk_add_f32 v[146:147], v[146:147], v[146:147] op_sel_hi:[0,1]
	v_pk_add_f32 v[142:143], v[142:143], v[142:143] op_sel_hi:[0,1]
	v_mul_f32_e32 v142, v58, v58
	v_pk_fma_f32 v[144:145], v[58:59], v[58:59], v[142:143] op_sel_hi:[1,1,0]
	v_mul_f32_e32 v142, v60, v60
	v_pk_fma_f32 v[148:149], v[60:61], v[60:61], v[142:143] op_sel_hi:[1,1,0]
	v_mul_f32_e32 v144, v46, v46
	v_mul_f32_e32 v148, v47, v47
	v_mul_f32_e32 v146, v48, v48
	v_mul_f32_e32 v142, v49, v49
	v_pk_add_f32 v[144:145], v[144:145], v[148:149]
	v_pk_add_f32 v[142:143], v[146:147], v[142:143]
	s_mov_b32 s0, 0xf800000
	v_pk_add_f32 v[142:143], v[144:145], v[142:143]
	v_pk_add_f32 v[56:57], v[56:57], 1.0 op_sel_hi:[1,0]
	v_add_f32_e32 v141, v142, v143
	ds_bpermute_b32 v142, v116, v141
	v_mov_b32_e32 v143, 0x358637bd
	v_pk_add_f32 v[54:55], v[54:55], 1.0 op_sel_hi:[1,0]
	v_pk_add_f32 v[40:41], v[40:41], 1.0 op_sel_hi:[1,0]
	v_pk_add_f32 v[38:39], v[38:39], 1.0 op_sel_hi:[1,0]
	s_waitcnt lgkmcnt(0)
	v_add_f32_e32 v141, v141, v142
	ds_bpermute_b32 v142, v117, v141
	v_pk_add_f32 v[36:37], v[36:37], 1.0 op_sel_hi:[1,0]
	v_pk_add_f32 v[34:35], v[34:35], 1.0 op_sel_hi:[1,0]
	v_pk_add_f32 v[24:25], v[24:25], 1.0 op_sel_hi:[1,0]
	v_pk_add_f32 v[22:23], v[22:23], 1.0 op_sel_hi:[1,0]
	s_waitcnt lgkmcnt(0)
	v_add_f32_e32 v141, v141, v142
	ds_bpermute_b32 v142, v152, v141
	s_nop 0
	s_nop 0
	s_nop 0
	s_nop 0
	s_waitcnt lgkmcnt(0)
	v_add_f32_e32 v141, v141, v142
	ds_bpermute_b32 v142, v153, v141
	s_nop 0
	s_nop 0
	s_nop 0
	s_nop 0
	s_waitcnt lgkmcnt(0)
	v_add_f32_e32 v141, v141, v142
	ds_bpermute_b32 v142, v154, v141
	s_nop 0
	s_waitcnt lgkmcnt(0)
	v_add_f32_e32 v141, v141, v142
	ds_bpermute_b32 v142, v155, v141
	s_waitcnt lgkmcnt(0)
	v_add_f32_e32 v141, v141, v142
	v_fmamk_f32 v141, v141, 0x3a800000, v143
	v_mul_f32_e32 v142, 0x4f800000, v141
	v_cmp_gt_f32_e32 vcc, s0, v141
	v_mov_b32_e32 v143, 0x260
	s_nop 0
	v_cndmask_b32_e32 v141, v141, v142, vcc
	v_sqrt_f32_e32 v142, v141
	s_nop 0
	v_add_u32_e32 v144, -1, v142
	v_add_u32_e32 v145, 1, v142
	v_fma_f32 v146, -v144, v142, v141
	v_fma_f32 v147, -v145, v142, v141
	v_cmp_ge_f32_e64 s[0:1], 0, v146
	s_nop 1
	v_cndmask_b32_e64 v142, v142, v144, s[0:1]
	v_cmp_lt_f32_e64 s[0:1], 0, v147
	s_nop 0
	s_nop 0
	v_cndmask_b32_e64 v142, v142, v145, s[0:1]
	v_mul_f32_e32 v144, 0x37800000, v142
	v_cndmask_b32_e32 v142, v142, v144, vcc
	v_cmp_class_f32_e32 vcc, v141, v143
	s_nop 1
	v_cndmask_b32_e32 v141, v142, v141, vcc
	v_div_scale_f32 v142, s[0:1], v141, v141, 1.0
	v_rcp_f32_e32 v143, v142
	v_div_scale_f32 v144, vcc, 1.0, v141, 1.0
	v_readlane_b32 s0, v253, 30
	v_fma_f32 v145, -v142, v143, 1.0
	v_fmac_f32_e32 v143, v145, v143
	v_mul_f32_e32 v145, v144, v143
	v_fma_f32 v146, -v142, v145, v144
	v_fmac_f32_e32 v145, v146, v143
	v_fma_f32 v142, -v142, v145, v144
	v_div_fmas_f32 v142, v142, v143, v145
	v_div_fixup_f32 v142, v142, v141, 1.0
	v_pk_mul_f32 v[52:53], v[52:53], v[142:143] op_sel_hi:[1,0]
	v_pk_mul_f32 v[50:51], v[50:51], v[142:143] op_sel_hi:[1,0]
	v_pk_mul_f32 v[52:53], v[4:5], v[52:53]
	v_pk_mul_f32 v[50:51], v[2:3], v[50:51]
	v_pk_fma_f32 v[44:45], v[56:57], v[52:53], v[44:45]
	v_pk_fma_f32 v[42:43], v[54:55], v[50:51], v[42:43]
	v_readlane_b32 s1, v253, 31
	v_cvt_pk_bf16_f32 v42, v42, v43
	v_cvt_pk_bf16_f32 v43, v44, v45
	global_store_dwordx2 v[114:115], v[42:43], off offset:-1024
	v_pk_mul_f32 v[42:43], v[64:65], v[142:143] op_sel_hi:[1,0]
	v_pk_mul_f32 v[44:45], v[62:63], v[142:143] op_sel_hi:[1,0]
	v_pk_mul_f32 v[42:43], v[8:9], v[42:43]
	v_pk_mul_f32 v[44:45], v[6:7], v[44:45]
	v_pk_fma_f32 v[32:33], v[40:41], v[42:43], v[32:33]
	v_pk_fma_f32 v[30:31], v[38:39], v[44:45], v[30:31]
	s_nop 0
	v_cvt_pk_bf16_f32 v30, v30, v31
	v_cvt_pk_bf16_f32 v31, v32, v33
	global_store_dwordx2 v[114:115], v[30:31], off offset:-512
	v_pk_mul_f32 v[30:31], v[60:61], v[142:143] op_sel_hi:[1,0]
	v_pk_mul_f32 v[32:33], v[58:59], v[142:143] op_sel_hi:[1,0]
	v_pk_mul_f32 v[30:31], v[12:13], v[30:31]
	v_pk_mul_f32 v[32:33], v[10:11], v[32:33]
	v_pk_fma_f32 v[28:29], v[36:37], v[30:31], v[28:29]
	v_pk_fma_f32 v[26:27], v[34:35], v[32:33], v[26:27]
	s_nop 0
	v_cvt_pk_bf16_f32 v26, v26, v27
	v_cvt_pk_bf16_f32 v27, v28, v29
	global_store_dwordx2 v[114:115], v[26:27], off
	v_pk_mul_f32 v[26:27], v[48:49], v[142:143] op_sel_hi:[1,0]
	v_pk_mul_f32 v[28:29], v[46:47], v[142:143] op_sel_hi:[1,0]
	v_pk_mul_f32 v[26:27], v[16:17], v[26:27]
	v_pk_mul_f32 v[28:29], v[14:15], v[28:29]
	v_pk_fma_f32 v[20:21], v[24:25], v[26:27], v[20:21]
	v_pk_fma_f32 v[18:19], v[22:23], v[28:29], v[18:19]
	s_nop 0
	v_cvt_pk_bf16_f32 v18, v18, v19
	v_cvt_pk_bf16_f32 v19, v20, v21
	global_store_dwordx2 v[114:115], v[18:19], off offset:512
	v_lshl_add_u64 v[114:115], v[114:115], 0, s[0:1]
	s_add_i32 s4, s4, s90
	s_cmp_lt_i32 s4, 0x8000
	s_cbranch_scc0 .Lnorm_done
	s_branch .Lnorm_loop
.Lnorm_done:
.LBB0_264:
	s_waitcnt vmcnt(0)
	s_barrier
	s_and_saveexec_b64 s[0:1], s[70:71]
	s_cbranch_execz .LBB0_316
	v_readlane_b32 s4, v253, 40
	s_mov_b64 s[2:3], 0
	s_mov_b32 s18, s68
	v_mov_b32_e32 v0, s4
	s_waitcnt vmcnt(0) expcnt(0) lgkmcnt(0)
	ds_read_b32 v3, v0
	v_readlane_b32 s4, v253, 41
	s_lshl_b64 s[2:3], s[2:3], 2
	s_add_u32 s2, s74, s2
	v_mov_b32_e32 v0, s4
	ds_read_b32 v0, v0
	s_waitcnt lgkmcnt(1)
	v_cmp_ne_u32_e32 vcc, 0, v3
	s_addc_u32 s3, s75, s3
	s_cbranch_vccnz .LBB0_280
	s_add_u32 s4, s2, 0x1000
	s_addc_u32 s5, s3, 0
	s_add_u32 s6, s2, 0x1100
	s_addc_u32 s7, s3, 0
	s_add_u32 s8, s2, 0x1200
	s_addc_u32 s9, s3, 0
	s_add_u32 s10, s2, 0x1300
	s_addc_u32 s11, s3, 0
	s_mov_b32 s19, 1
	s_branch .LBB0_268
